# P3 delta items: conv weights staged once per workgroup in LDS (ds_read_b128 per item), on top of the DPP reductions
# speedup vs baseline: 1.0043x; 1.0043x over previous
.Lp3pre_now:
	v_readfirstlane_b32 s2, v0
	s_lshr_b32 s2, s2, 6
	s_mul_i32 s3, s2, s48
	s_add_i32 s3, s3, s41
	s_and_b32 s71, s3, 0xffffffc0
	s_and_b32 s68, s53, 7
	s_mul_i32 s88, s2, s82
	s_mov_b32 s89, 0
	s_lshl_b32 s3, s2, 10
	s_add_i32 s3, s3, 0x1c200
	v_lshl_add_u64 v[56:57], v[80:81], 0, s[88:89]
	v_add_u32_e32 v58, s3, v184
	v_or_b32_e32 v34, s71, v1
	v_ashrrev_i32_e32 v35, 31, v34
	v_readlane_b32 s2, v250, 12
	v_lshlrev_b64 v[34:35], 7, v[34:35]
	v_readlane_b32 s3, v250, 13
	s_lshl_b32 s80, s68, 2
	v_mov_b32_e32 v38, s80
	v_lshl_add_u64 v[34:35], s[2:3], 0, v[34:35]
	v_readlane_b32 s2, v250, 4
	v_readlane_b32 s3, v250, 5
	v_lshl_add_u64 v[34:35], v[34:35], 0, s[80:81]
	s_nop 3
	global_load_dword v39, v38, s[2:3]
	global_load_dword v37, v[34:35], off
	global_load_dword v40, v[34:35], off offset:64
	global_load_dword v36, v[34:35], off offset:32
	s_nop 0
	global_load_dword v38, v38, s[78:79]
	s_add_u32 s68, s78, s80
	s_addc_u32 s69, s79, 0
	s_add_u32 s88, s2, s80
	s_mov_b32 s2, 0x41a00000
	s_addc_u32 s89, s3, 0
	global_load_dword v59, v[34:35], off offset:96
	global_load_dword v60, v89, s[88:89] offset:32
	global_load_dword v61, v89, s[68:69] offset:32
	s_waitcnt vmcnt(5)
	v_add_f32_e32 v39, v40, v39
	v_cmp_nlt_f32_e32 vcc, s2, v39
	s_and_saveexec_b64 s[2:3], vcc
	s_cbranch_execz .Lp3pre_330
	v_mul_f32_e32 v39, 0x3fb8aa3b, v39
	v_exp_f32_e32 v39, v39
	s_mov_b32 s71, 0x3f2aaaab
	v_add_f32_e32 v42, 1.0, v39
	v_frexp_mant_f32_e32 v44, v42
	v_cvt_f64_f32_e32 v[40:41], v42
	v_frexp_exp_i32_f64_e32 v40, v[40:41]
	v_cmp_gt_f32_e32 vcc, s71, v44
	v_add_f32_e32 v43, -1.0, v42
	v_sub_f32_e32 v45, v43, v42
	v_subbrev_co_u32_e32 v48, vcc, 0, v40, vcc
	v_sub_u32_e32 v40, 0, v48
	v_sub_f32_e32 v43, v39, v43
	v_add_f32_e32 v45, 1.0, v45
	v_ldexp_f32 v41, v42, v40
	v_add_f32_e32 v43, v43, v45
	v_add_f32_e32 v42, -1.0, v41
	v_add_f32_e32 v44, 1.0, v41
	v_ldexp_f32 v40, v43, v40
	v_add_f32_e32 v43, 1.0, v42
	v_add_f32_e32 v45, -1.0, v44
	v_sub_f32_e32 v43, v41, v43
	v_sub_f32_e32 v41, v41, v45
	v_add_f32_e32 v43, v40, v43
	v_add_f32_e32 v40, v40, v41
	v_add_f32_e32 v49, v44, v40
	v_rcp_f32_e32 v51, v49
	v_sub_f32_e32 v41, v49, v44
	v_sub_f32_e32 v50, v40, v41
	v_add_f32_e32 v41, v42, v43
	v_mul_f32_e32 v53, v41, v51
	v_sub_f32_e32 v40, v41, v42
	v_mul_f32_e32 v42, v49, v53
	v_fma_f32 v44, v53, v49, -v42
	v_fmac_f32_e32 v44, v53, v50
	v_sub_f32_e32 v52, v43, v40
	v_add_f32_e32 v40, v42, v44
	v_sub_f32_e32 v43, v41, v40
	v_pk_add_f32 v[46:47], v[40:41], v[42:43] neg_lo:[0,1] neg_hi:[0,1]
	v_mov_b32_e32 v45, v40
	v_pk_add_f32 v[40:41], v[46:47], v[44:45] neg_lo:[0,1] neg_hi:[0,1]
	s_mov_b32 s71, 0x3f317218
	v_add_f32_e32 v41, v52, v41
	v_add_f32_e32 v40, v40, v41
	v_add_f32_e32 v41, v43, v40
	v_mul_f32_e32 v52, v51, v41
	v_mul_f32_e32 v42, v49, v52
	v_fma_f32 v44, v52, v49, -v42
	v_fmac_f32_e32 v44, v52, v50
	v_sub_f32_e32 v43, v43, v41
	v_add_f32_e32 v49, v40, v43
	v_add_f32_e32 v40, v42, v44
	v_sub_f32_e32 v43, v41, v40
	v_pk_add_f32 v[46:47], v[40:41], v[42:43] neg_lo:[0,1] neg_hi:[0,1]
	v_mov_b32_e32 v45, v40
	v_pk_add_f32 v[40:41], v[46:47], v[44:45] neg_lo:[0,1] neg_hi:[0,1]
	s_nop 0
	v_add_f32_e32 v41, v49, v41
	v_add_f32_e32 v40, v40, v41
	v_add_f32_e32 v41, v53, v52
	v_add_f32_e32 v40, v43, v40
	v_sub_f32_e32 v42, v41, v53
	v_mul_f32_e32 v40, v51, v40
	v_sub_f32_e32 v42, v52, v42
	v_add_f32_e32 v42, v42, v40
	v_add_f32_e32 v44, v41, v42
	v_mul_f32_e32 v45, v44, v44
	v_fmamk_f32 v40, v45, 0x3e9b6dac, v212
	v_fmaak_f32 v95, v45, v40, 0x3f2aaada
	v_cvt_f32_i32_e32 v40, v48
	v_sub_f32_e32 v41, v44, v41
	v_sub_f32_e32 v41, v42, v41
	v_ldexp_f32 v46, v41, 1
	v_mul_f32_e32 v41, v44, v45
	v_ldexp_f32 v43, v44, 1
	v_pk_mul_f32 v[44:45], v[40:41], v[94:95]
	s_nop 0
	v_fma_f32 v42, v40, s71, -v44
	v_fmac_f32_e32 v42, 0xb102e308, v40
	v_pk_add_f32 v[40:41], v[44:45], v[42:43]
	s_mov_b32 s71, 0x7f800000
	v_sub_f32_e32 v43, v41, v43
	v_sub_f32_e32 v43, v45, v43
	v_add_f32_e32 v47, v46, v43
	v_mov_b32_e32 v46, v44
	v_pk_add_f32 v[44:45], v[40:41], v[44:45] neg_lo:[0,1] neg_hi:[0,1]
	v_pk_add_f32 v[48:49], v[40:41], v[46:47]
	v_mov_b32_e32 v43, v40
	v_mov_b32_e32 v45, v49
	v_pk_add_f32 v[50:51], v[42:43], v[44:45] neg_lo:[0,1] neg_hi:[0,1]
	v_pk_add_f32 v[42:43], v[42:43], v[44:45]
	v_mov_b32_e32 v46, v47
	v_pk_add_f32 v[44:45], v[42:43], v[40:41] op_sel:[1,0] op_sel_hi:[0,1] neg_lo:[0,1] neg_hi:[0,1]
	v_pk_add_f32 v[52:53], v[48:49], v[44:45] op_sel_hi:[1,0] neg_lo:[0,1] neg_hi:[0,1]
	v_mov_b32_e32 v48, v49
	v_mov_b32_e32 v49, v43
	v_pk_mov_b32 v[44:45], v[40:41], v[44:45] op_sel:[1,0]
	v_mov_b32_e32 v47, v40
	v_pk_add_f32 v[44:45], v[48:49], v[44:45] neg_lo:[0,1] neg_hi:[0,1]
	v_mov_b32_e32 v52, v50
	v_pk_add_f32 v[40:41], v[46:47], v[44:45] neg_lo:[0,1] neg_hi:[0,1]
	v_mov_b32_e32 v51, v43
	v_pk_add_f32 v[44:45], v[52:53], v[40:41]
	v_cmp_neq_f32_e32 vcc, s71, v39
	v_pk_add_f32 v[46:47], v[44:45], v[44:45] op_sel:[0,1] op_sel_hi:[1,0]
	s_mov_b32 s71, 0x33800000
	v_pk_add_f32 v[42:43], v[42:43], v[46:47] op_sel:[1,0] op_sel_hi:[0,1]
	v_mov_b32_e32 v45, v42
	v_pk_add_f32 v[48:49], v[44:45], v[50:51] neg_lo:[0,1] neg_hi:[0,1]
	v_mov_b32_e32 v41, v46
	v_sub_f32_e32 v43, v44, v48
	v_pk_add_f32 v[40:41], v[40:41], v[48:49] neg_lo:[0,1] neg_hi:[0,1]
	v_sub_f32_e32 v43, v50, v43
	v_add_f32_e32 v40, v40, v43
	v_add_f32_e32 v40, v40, v41
	v_add_f32_e32 v40, v42, v40
	v_cndmask_b32_e32 v40, v225, v40, vcc
	v_cmp_ngt_f32_e32 vcc, -1.0, v39
	s_nop 1
	v_cndmask_b32_e32 v40, v226, v40, vcc
	v_cmp_neq_f32_e32 vcc, -1.0, v39
	s_nop 1
	v_cndmask_b32_e32 v40, v227, v40, vcc
	v_cmp_lt_f32_e64 vcc, |v39|, s71
	s_nop 1
	v_cndmask_b32_e32 v39, v40, v39, vcc

.LBB0_313:
	v_add_u32_e32 v230, 0, v146
	v_add_u32_e32 v34, s49, v146
	ds_write_b128 v230, v[234:237] offset:54272
	ds_write_b128 v209, v[234:237] offset:54272
	ds_write_b128 v210, v[234:237] offset:54272
	s_and_saveexec_b64 s[2:3], s[42:43]
	ds_write_b128 v34, v[30:33] offset:6144
	s_or_b64 exec, exec, s[2:3]
	s_and_saveexec_b64 s[2:3], s[44:45]
	ds_write_b128 v34, v[30:33] offset:14336
	s_or_b64 exec, exec, s[2:3]
	s_and_b32 s68, s53, 7
	s_lshl_b32 s69, s68, 7
	v_and_b32_e32 v88, 31, v0
	v_lshlrev_b32_e32 v88, 4, v88
	v_add_u32_e32 v88, 0x26a00, v88
	ds_read_b128 v[34:37], v88
	ds_read_b128 v[38:41], v88 offset:512
	ds_read_b128 v[50:53], v88 offset:1024
	ds_read_b128 v[54:57], v88 offset:1536
	ds_read_b128 v[58:61], v88 offset:2048
	ds_read_b128 v[42:45], v88 offset:2560
	ds_read_b128 v[46:49], v88 offset:3072
	ds_read_b128 v[62:65], v88 offset:3584
	s_waitcnt vmcnt(0)
	v_lshlrev_b32_e32 v122, 16, v2
	v_and_b32_e32 v123, 0xffff0000, v2
	v_lshlrev_b32_e32 v66, 16, v6
	v_and_b32_e32 v68, 0xffff0000, v6
	v_mov_b32_e32 v67, v122
	v_mov_b32_e32 v69, v123
	v_lshlrev_b32_e32 v96, 16, v10
	v_and_b32_e32 v97, 0xffff0000, v10
	v_lshlrev_b32_e32 v104, 16, v14
	v_and_b32_e32 v105, 0xffff0000, v14
	v_mov_b32_e32 v124, v104
	v_mov_b32_e32 v125, v96
	v_mov_b32_e32 v126, v105
	v_mov_b32_e32 v127, v97
	v_lshlrev_b32_e32 v88, 16, v9
	v_lshlrev_b32_e32 v108, 16, v7
	v_and_b32_e32 v120, 0xffff0000, v7
	v_lshlrev_b32_e32 v109, 16, v3
	v_and_b32_e32 v121, 0xffff0000, v3
	v_lshlrev_b32_e32 v98, 16, v11
	v_and_b32_e32 v99, 0xffff0000, v11
	v_and_b32_e32 v107, 0xffff0000, v15
	v_lshlrev_b32_e32 v106, 16, v15
	v_lshlrev_b32_e32 v100, 16, v12
	v_lshlrev_b32_e32 v114, 16, v16
	v_mov_b32_e32 v128, v106
	v_mov_b32_e32 v129, v98
	v_mov_b32_e32 v130, v107
	v_mov_b32_e32 v131, v99
	v_and_b32_e32 v101, 0xffff0000, v12
	v_and_b32_e32 v115, 0xffff0000, v16
	v_lshlrev_b32_e32 v102, 16, v8
	v_and_b32_e32 v118, 0xffff0000, v8
	v_and_b32_e32 v110, 0xffff0000, v9
	v_and_b32_e32 v111, 0xffff0000, v5
	s_and_b32 s71, s41, 0xffffffc0
	s_waitcnt lgkmcnt(7)
	v_mul_f32_e32 v133, v36, v88
	s_waitcnt lgkmcnt(6)
	v_mov_b32_e32 v134, v38
	v_mov_b32_e32 v136, v39
	v_mov_b32_e32 v138, v40
	s_waitcnt lgkmcnt(5)
	v_mov_b32_e32 v135, v50
	v_mov_b32_e32 v137, v51
	v_pk_mul_f32 v[66:67], v[134:135], v[66:67]
	v_pk_mul_f32 v[68:69], v[136:137], v[68:69]
	v_mov_b32_e32 v248, v66
	v_mov_b32_e32 v249, v68
	v_pk_add_f32 v[248:249], v[248:249], 0 op_sel_hi:[1,0]
	v_mov_b32_e32 v68, v67
	s_waitcnt lgkmcnt(4)
	v_mov_b32_e32 v142, v54
	v_mov_b32_e32 v232, v55
	v_pk_add_f32 v[66:67], v[248:249], v[68:69]
	s_waitcnt lgkmcnt(3)
	v_mov_b32_e32 v143, v58
	v_mov_b32_e32 v233, v59
	v_pk_mul_f32 v[142:143], v[142:143], v[124:125]
	v_pk_mul_f32 v[232:233], v[232:233], v[126:127]
	v_mov_b32_e32 v68, v142
	v_mov_b32_e32 v69, v232
	v_pk_add_f32 v[66:67], v[66:67], v[68:69]
	v_mov_b32_e32 v232, v143
	v_pk_add_f32 v[66:67], v[66:67], v[232:233]
	v_mov_b32_e32 v140, v41
	v_mul_f32_e32 v68, 0xbfb8aa3b, v66
	v_exp_f32_e32 v68, v68
	v_mul_f32_e32 v69, 0xbfb8aa3b, v67
	v_exp_f32_e32 v88, v69
	v_mov_b32_e32 v139, v52
	v_add_f32_e32 v68, 1.0, v68
	v_rcp_f32_e32 v142, v68
	v_add_f32_e32 v68, 1.0, v88
	v_rcp_f32_e32 v143, v68
	v_mov_b32_e32 v141, v53
	v_pk_mul_f32 v[138:139], v[138:139], v[108:109]
	v_pk_mul_f32 v[140:141], v[140:141], v[120:121]
	v_mov_b32_e32 v134, v56
	v_mov_b32_e32 v136, v57
	v_mov_b32_e32 v135, v60
	v_mov_b32_e32 v137, v61
	v_pk_mul_f32 v[66:67], v[66:67], v[142:143]
	v_mov_b32_e32 v142, v140
	v_mov_b32_e32 v143, v138
	s_waitcnt lgkmcnt(2)
	v_mov_b32_e32 v238, v42
	v_pk_mul_f32 v[128:129], v[134:135], v[128:129]
	v_pk_mul_f32 v[130:131], v[136:137], v[130:131]
	s_waitcnt lgkmcnt(1)
	v_mov_b32_e32 v239, v46
	v_mov_b32_e32 v124, v114
	v_mov_b32_e32 v125, v100
	v_pk_add_f32 v[142:143], v[142:143], 0 op_sel_hi:[1,0]
	v_mov_b32_e32 v138, v141
	v_pk_mul_f32 v[134:135], v[238:239], v[124:125]
	v_mov_b32_e32 v124, v43
	v_mov_b32_e32 v125, v47
	v_mov_b32_e32 v126, v115
	v_mov_b32_e32 v127, v101
	v_pk_add_f32 v[138:139], v[142:143], v[138:139]
	v_mov_b32_e32 v140, v130
	v_mov_b32_e32 v141, v128
	v_pk_mul_f32 v[136:137], v[124:125], v[126:127]
	v_lshlrev_b32_e32 v124, 16, v4
	v_pk_add_f32 v[138:139], v[138:139], v[140:141]
	v_mov_b32_e32 v128, v131
	v_and_b32_e32 v125, 0xffff0000, v4
	v_mov_b32_e32 v126, v34
	s_waitcnt lgkmcnt(0)
	v_mov_b32_e32 v127, v62
	v_mov_b32_e32 v103, v124
	v_pk_add_f32 v[128:129], v[138:139], v[128:129]
	v_pk_mul_f32 v[238:239], v[126:127], v[102:103]
	v_mov_b32_e32 v102, v35
	v_mov_b32_e32 v103, v63
	v_mov_b32_e32 v119, v125
	v_mul_f32_e32 v68, 0xbfb8aa3b, v129
	v_pk_mul_f32 v[240:241], v[102:103], v[118:119]
	v_exp_f32_e32 v68, v68
	v_mul_f32_e32 v88, 0xbfb8aa3b, v128
	v_exp_f32_e32 v88, v88
	v_mov_b32_e32 v140, v240
	v_mov_b32_e32 v141, v238
	v_pk_add_f32 v[140:141], v[140:141], 0 op_sel_hi:[1,0]
	v_mov_b32_e32 v238, v241
	v_pk_add_f32 v[140:141], v[140:141], v[238:239]
	v_mov_b32_e32 v142, v136
	v_mov_b32_e32 v143, v134
	v_add_f32_e32 v68, 1.0, v68
	v_pk_add_f32 v[140:141], v[140:141], v[142:143]
	v_mov_b32_e32 v134, v137
	v_rcp_f32_e32 v139, v68
	v_add_f32_e32 v68, 1.0, v88
	v_pk_add_f32 v[134:135], v[140:141], v[134:135]
	v_rcp_f32_e32 v138, v68
	v_mul_f32_e32 v68, 0xbfb8aa3b, v135
	v_exp_f32_e32 v68, v68
	v_and_b32_e32 v103, 0xffff0000, v13
	v_and_b32_e32 v119, 0xffff0000, v17
	v_mov_b32_e32 v232, v37
	v_mov_b32_e32 v233, v65
	v_mov_b32_e32 v126, v45
	v_mov_b32_e32 v127, v49
	v_mov_b32_e32 v246, v119
	v_mov_b32_e32 v247, v103
	v_pk_mul_f32 v[232:233], v[232:233], v[110:111]
	v_pk_mul_f32 v[246:247], v[126:127], v[246:247]
	v_lshlrev_b32_e32 v126, 16, v5
	v_add_f32_e32 v68, 1.0, v68
	v_mov_b32_e32 v132, v232
	v_lshlrev_b32_e32 v118, 16, v17
	v_mul_f32_e32 v69, v64, v126
	v_rcp_f32_e32 v137, v68
	v_pk_add_f32 v[132:133], v[132:133], 0 op_sel_hi:[1,0]
	v_mov_b32_e32 v68, v233
	v_lshlrev_b32_e32 v102, 16, v13
	v_mul_f32_e32 v245, v44, v118
	v_pk_add_f32 v[68:69], v[132:133], v[68:69]
	v_mov_b32_e32 v244, v246
	v_mul_f32_e32 v243, v48, v102
	v_pk_add_f32 v[68:69], v[68:69], v[244:245]
	v_mov_b32_e32 v242, v247
	v_mul_f32_e32 v88, 0xbfb8aa3b, v134
	v_pk_add_f32 v[68:69], v[68:69], v[242:243]
	v_exp_f32_e32 v88, v88
	v_mul_f32_e32 v91, 0xbfb8aa3b, v69
	v_exp_f32_e32 v91, v91
	v_mul_f32_e32 v95, 0xbfb8aa3b, v68
	v_exp_f32_e32 v95, v95
	v_add_f32_e32 v88, 1.0, v88
	v_rcp_f32_e32 v136, v88
	v_add_f32_e32 v88, 1.0, v91
	v_rcp_f32_e32 v133, v88
	v_add_f32_e32 v88, 1.0, v95
	v_pk_mul_f32 v[130:131], v[66:67], v[66:67]
	v_pk_mul_f32 v[128:129], v[128:129], v[138:139]
	v_rcp_f32_e32 v132, v88
	v_pk_mul_f32 v[138:139], v[128:129], v[128:129]
	v_add_f32_e32 v88, v130, v131
	v_pk_mul_f32 v[134:135], v[134:135], v[136:137]
	v_add_f32_e32 v88, v139, v88
	v_pk_mul_f32 v[136:137], v[134:135], v[134:135]
	v_add_f32_e32 v88, v138, v88
	v_pk_mul_f32 v[68:69], v[68:69], v[132:133]
	v_add_f32_e32 v88, v137, v88
	v_pk_mul_f32 v[132:133], v[68:69], v[68:69]
	v_add_f32_e32 v88, v136, v88
	v_add_f32_e32 v88, v133, v88
	v_add_f32_e32 v88, v132, v88
	s_nop 1
	v_add_f32_dpp v88, v88, v88 quad_perm:[1,0,3,2] row_mask:0xf bank_mask:0xf
	s_nop 1
	v_add_f32_dpp v88, v88, v88 quad_perm:[2,3,0,1] row_mask:0xf bank_mask:0xf
	s_nop 1
	v_add_f32_dpp v88, v88, v88 row_ror:4 row_mask:0xf bank_mask:0xf
	s_nop 1
	v_add_f32_dpp v88, v88, v88 row_ror:8 row_mask:0xf bank_mask:0xf
	v_add_f32_e32 v88, 0x358637bd, v88
	v_mul_f32_e32 v91, 0x4b800000, v88
	v_cmp_gt_f32_e32 vcc, s52, v88
	s_nop 1
	v_cndmask_b32_e32 v88, v88, v91, vcc
	v_rsq_f32_e32 v88, v88
	s_nop 0
	v_mul_f32_e32 v91, 0x45800000, v88
	v_cndmask_b32_e32 v88, v88, v91, vcc
	v_mul_f32_e32 v88, v179, v88
	v_mul_f32_e32 v116, v66, v88
	v_mul_f32_e32 v232, v67, v88
	v_mul_f32_e32 v112, v129, v88
	v_mul_f32_e32 v231, v128, v88
	v_mul_f32_e32 v110, v135, v88
	v_mul_f32_e32 v95, v134, v88
	v_mul_f32_e32 v108, v69, v88
	v_mul_f32_e32 v91, v68, v88
	v_cvt_pk_bf16_f32 v66, v116, v232
	v_cvt_pk_bf16_f32 v67, v112, v231
	v_cvt_pk_bf16_f32 v68, v110, v95
	v_cvt_pk_bf16_f32 v69, v108, v91
	v_lshlrev_b32_e32 v88, 1, v86
	ds_write_b128 v224, v[66:69]
	s_and_saveexec_b64 s[2:3], s[38:39]
	s_cbranch_execz .LBB0_319
	v_add_u32_e32 v128, s71, v180
	v_ashrrev_i32_e32 v129, 31, v128
	v_lshlrev_b64 v[128:129], 11, v[128:129]
	v_lshl_add_u64 v[128:129], s[72:73], 0, v[128:129]
	s_lshl_b32 s80, s69, 1
	v_lshl_add_u64 v[128:129], v[128:129], 0, s[80:81]
	v_lshl_add_u64 v[128:129], v[128:129], 0, v[88:89]
	global_store_dwordx4 v[128:129], v[66:69], off
